# PEER pass V tail: reduce-scatter reduction (permlane32_swap, permlane16_swap, keep/send + row_ror:8) instead of all-reduce + 4-way select; cvt_pk_bf16 pack
# speedup vs baseline: 1.0137x; 1.0074x over previous
; __device__ __forceinline__ void p8_peer_gather(Frame& F) {
;     ...
;     { const unsigned vo0 = sub * 16;
; #pragma unroll
;       for (int g = 0; g < 4; ++g) { const v4u iv = *(const v4u*)(idx_s + wave * 128 + pg * 16 + 4 * g);
;           d[4 * g] = *(const v4u*)(VQ + (size_t)(iv.x + vo0)); d[4 * g + 1] = *(const v4u*)(VQ + (size_t)(iv.y + vo0)); d[4 * g + 2] = *(const v4u*)(VQ + (size_t)(iv.z + vo0)); d[4 * g + 3] = *(const v4u*)(VQ + (size_t)(iv.w + vo0)); } }
;     for (int s_ = 0; s_ < 16 * NREP_V; ++s_) { const int s = s_ & 15;
;         const unsigned voff = s * 128 + sub * 16;
;         const int jend = (s & 7) == wave ? 72 : 64;
; #pragma unroll 1
;         for (int jj = wave; jj < jend; jj += 8) { const int j = jj < 64 ? jj : 64;
;             const bool nsame = jj + 8 < jend, nlast = !nsame && !(s_ + 1 < 16 * NREP_V);
;             const int nj = nsame ? (jj + 8 < 64 ? jj + 8 : 64) : (nlast ? j : wave);
;             const unsigned noff = (nsame || nlast) ? voff : ((s + 1) & 15) * 128 + sub * 16;
;             bf16* yp = (bf16*)X1B + ((size_t)F.bid + 256 * j) * DM + 256 * s + 32 * sub + 16 * (pg >> 2) + 4 * (pg & 3);
;             const bool wr = s_ >= 16 * (NREP_V - 1);
;             v2u xw4 = {0u, 0u};
;             if (wr) xw4 = *(const v2u*)yp;
.LBB0_2581:
	s_or_b64 exec, exec, s[4:5]
	s_waitcnt lgkmcnt(0)
	s_barrier
	ds_read_b128 v[2:5], v80
	ds_read_b128 v[10:13], v80 offset:16
	ds_read_b128 v[18:21], v80 offset:32
	ds_read_b128 v[40:43], v80 offset:48
	v_readlane_b32 s0, v253, 32
	v_readlane_b32 s2, v253, 34
	v_readlane_b32 s3, v253, 35
	s_add_u32 s12, s2, 0x3b600000
	s_addc_u32 s13, s3, 0
	s_waitcnt lgkmcnt(3)
	v_add_u32_e32 v6, v2, v93
	v_add_u32_e32 v7, v3, v93
	v_add_u32_e32 v8, v4, v93
	v_add_u32_e32 v9, v5, v93
	s_waitcnt lgkmcnt(2)
	v_add_u32_e32 v14, v10, v93
	v_add_u32_e32 v15, v11, v93
	v_add_u32_e32 v16, v12, v93
	v_add_u32_e32 v17, v13, v93
	s_waitcnt lgkmcnt(1)
	v_add_u32_e32 v22, v18, v93
	v_add_u32_e32 v23, v19, v93
	v_add_u32_e32 v32, v20, v93
	v_add_u32_e32 v33, v21, v93
	s_waitcnt lgkmcnt(0)
	v_add_u32_e32 v40, v40, v93
	v_add_u32_e32 v41, v41, v93
	v_add_u32_e32 v64, v42, v93
	global_load_dwordx4 v[24:27], v6, s[12:13]
	global_load_dwordx4 v[0:3], v7, s[12:13]
	global_load_dwordx4 v[28:31], v8, s[12:13]
	s_nop 0
	global_load_dwordx4 v[4:7], v9, s[12:13]
	global_load_dwordx4 v[36:39], v14, s[12:13]
	s_nop 0
	global_load_dwordx4 v[8:11], v15, s[12:13]
	global_load_dwordx4 v[44:47], v16, s[12:13]
	s_nop 0
	global_load_dwordx4 v[12:15], v17, s[12:13]
	global_load_dwordx4 v[48:51], v22, s[12:13]
	s_nop 0
	global_load_dwordx4 v[16:19], v23, s[12:13]
	global_load_dwordx4 v[52:55], v32, s[12:13]
	s_nop 0
	global_load_dwordx4 v[20:23], v33, s[12:13]
	global_load_dwordx4 v[56:59], v40, s[12:13]
	s_nop 0
	global_load_dwordx4 v[32:35], v41, s[12:13]
	v_add_u32_e32 v65, v43, v93
	global_load_dwordx4 v[60:63], v64, s[12:13]
	global_load_dwordx4 v[40:43], v65, s[12:13]
	s_add_u32 s10, s2, 0x4a00000
	s_addc_u32 s11, s3, 0
	v_lshlrev_b32_e32 v64, 1, v90
	v_mov_b32_e32 v65, 0
	v_lshl_add_u64 v[66:67], s[10:11], 0, v[64:65]
	v_and_b32_e32 v64, 32, v88
	v_bfe_u32 v68, v92, 3, 2
	v_readlane_b32 s1, v253, 33
	v_lshl_add_u64 v[66:67], v[66:67], 0, v[64:65]
	v_lshlrev_b32_e32 v64, 3, v68
	v_lshl_add_u64 v[84:85], v[66:67], 0, v[64:65]
	s_mov_b32 s15, 0
	v_cmp_ne_u32_e64 s[0:1], 0, v68
	v_cmp_ne_u32_e64 s[4:5], 1, v68
	v_cmp_eq_u32_e64 s[6:7], 2, v68
	v_cmp_gt_u32_e64 s[8:9], 2, v68
	s_mov_b32 s16, 0x3f9837f0
	s_mov_b32 s42, 0xff00ff00
	s_mov_b32 s43, 0xff00ff00
	s_movk_i32 s2, 0x7fff
	v_mov_b32_e32 v95, 1
	s_mov_b32 s3, 0
	s_branch .LBB0_2583

; __device__ __forceinline__ void p8_peer_gather(Frame& F) {
;     ...
;         for (int jj = wave; jj < jend; jj += 8) { const int j = jj < 64 ? jj : 64;
;             const bool nsame = jj + 8 < jend, nlast = !nsame && !(s_ + 1 < 16 * NREP_V);
;             const int nj = nsame ? (jj + 8 < 64 ? jj + 8 : 64) : (nlast ? j : wave);
;             const unsigned noff = (nsame || nlast) ? voff : ((s + 1) & 15) * 128 + sub * 16;
;             bf16* yp = (bf16*)X1B + ((size_t)F.bid + 256 * j) * DM + 256 * s + 32 * sub + 16 * (pg >> 2) + 4 * (pg & 3);
;             const bool wr = s_ >= 16 * (NREP_V - 1);
;             v2u xw4 = {0u, 0u};
;             if (wr) xw4 = *(const v2u*)yp;
;             const f32x4 c0 = *(const f32x4*)(cf_s + j * 128 + pg * 16), c1 = *(const f32x4*)(cf_s + j * 128 + pg * 16 + 4), c2 = *(const f32x4*)(cf_s + j * 128 + pg * 16 + 8), c3 = *(const f32x4*)(cf_s + j * 128 + pg * 16 + 12);
;             const float cc[16] = {c0[0], c0[1], c0[2], c0[3], c1[0], c1[1], c1[2], c1[3], c2[0], c2[1], c2[2], c2[3], c3[0], c3[1], c3[2], c3[3]};
;             h16x2 ya[16];
; #pragma unroll
;             for (int e = 0; e < 16; ++e) ya[e] = (h16x2){(_Float16)0.f, (_Float16)0.f};
; #pragma unroll
;             for (int i = 0; i < 16; ++i) { const h16x2 cf2 = __builtin_bit_cast(h16x2, cc[i]);
; #pragma unroll
;                 for (int w = 0; w < 4; ++w) { ya[4 * w] += cf2 * __builtin_amdgcn_cvt_scalef32_pk_f16_fp4(d[i][w], 1.0f, 0); ya[4 * w + 1] += cf2 * __builtin_amdgcn_cvt_scalef32_pk_f16_fp4(d[i][w], 1.0f, 1);
;                     ya[4 * w + 2] += cf2 * __builtin_amdgcn_cvt_scalef32_pk_f16_fp4(d[i][w], 1.0f, 2); ya[4 * w + 3] += cf2 * __builtin_amdgcn_cvt_scalef32_pk_f16_fp4(d[i][w], 1.0f, 3); }
;                 d[i] = *(const v4u*)(VQ + (size_t)(idx_s[nj * 128 + pg * 16 + i] + noff)); }
;             h16x2 tt[8];
; #pragma unroll
;             for (int e = 0; e < 8; ++e) {
;                 const auto rr = __builtin_amdgcn_permlane32_swap(__builtin_bit_cast(unsigned, ya[e]), __builtin_bit_cast(unsigned, ya[e + 8]), false, false);
;                 h16x2 t = __builtin_bit_cast(h16x2, (unsigned)rr[0]) + __builtin_bit_cast(h16x2, (unsigned)rr[1]);
;                 t += __builtin_bit_cast(h16x2, xor16(__builtin_bit_cast(float, t)));
;                 t += __builtin_bit_cast(h16x2, xor8(__builtin_bit_cast(float, t)));
;                 tt[e] = t; }
.LBB0_2585:
	v_cvt_f32_f16_e32 v66, v68
	v_cvt_f32_f16_e32 v67, v69
	v_cvt_f32_f16_sdwa v69, v69 dst_sel:DWORD dst_unused:UNUSED_PAD src0_sel:WORD_1
	v_cvt_f32_f16_sdwa v68, v68 dst_sel:DWORD dst_unused:UNUSED_PAD src0_sel:WORD_1
	s_waitcnt vmcnt(16)
	v_lshlrev_b32_e32 v65, 16, v91
	v_lshlrev_b32_e32 v64, 16, v90
	v_pk_fma_f32 v[64:65], v[64:65], s[16:17], v[66:67] op_sel_hi:[1,0,1]
	v_and_b32_e32 v67, 0xffff0000, v91
	v_and_b32_e32 v66, 0xffff0000, v90
	v_pk_fma_f32 v[66:67], v[66:67], s[16:17], v[68:69] op_sel_hi:[1,0,1]
	v_cvt_pk_bf16_f32 v64, v64, v66
	v_cvt_pk_bf16_f32 v65, v65, v67
	s_and_b64 vcc, exec, s[20:21]
	global_store_dwordx2 v[88:89], v[64:65], off
	s_cbranch_vccnz .LBB0_2582
.LBB0_2586:
	s_min_i32 s28, s14, 64
	s_add_i32 s14, s14, 8
	s_cmp_ge_u32 s14, s17
	s_cselect_b64 s[20:21], -1, 0
	s_and_b64 s[22:23], s[18:19], exec
	s_cselect_b32 s29, s28, s74
	s_min_i32 s30, s14, 64
	s_cmp_lt_u32 s14, s17
	s_cselect_b64 s[22:23], -1, 0
	s_and_b64 s[24:25], s[22:23], exec
	s_cselect_b32 s24, s30, s29
	s_or_b64 s[22:23], s[18:19], s[22:23]
	s_and_b64 s[22:23], s[22:23], exec
	s_cselect_b32 s25, s26, s27
	s_lshl_b32 s22, s28, 8
	s_add_u32 s22, s22, s72
	s_addc_u32 s23, 0, s73
	s_lshl_b64 s[22:23], s[22:23], 13
	v_lshl_add_u64 v[88:89], v[86:87], 0, s[22:23]
	v_lshl_add_u32 v64, s28, 9, v94
	global_load_dwordx2 v[90:91], v[88:89], off
	ds_read_b128 v[98:101], v64 offset:33280
	ds_read_b128 v[80:83], v64 offset:33296
	ds_read_b128 v[72:75], v64 offset:33312
	ds_read_b128 v[64:67], v64 offset:33328
	s_waitcnt vmcnt(16)
	v_cvt_scalef32_pk_f16_fp4 v68, v24, 1.0
	s_waitcnt lgkmcnt(3)
	v_pk_fma_f16 v68, v68, v98, 0
	v_cvt_scalef32_pk_f16_fp4 v69, v24, 1.0 op_sel:[1,0,0]
	s_waitcnt vmcnt(15)
	v_cvt_scalef32_pk_f16_fp4 v105, v0, 1.0
	v_pk_fma_f16 v69, v69, v98, 0
	v_cvt_scalef32_pk_f16_fp4 v70, v24, 1.0 op_sel:[0,1,0]
	v_cvt_scalef32_pk_f16_fp4 v24, v24, 1.0 op_sel:[1,1,0]
	v_pk_fma_f16 v110, v105, v99, v68
	v_cvt_scalef32_pk_f16_fp4 v68, v0, 1.0 op_sel:[1,0,0]
	v_pk_fma_f16 v24, v24, v98, 0
	v_cvt_scalef32_pk_f16_fp4 v71, v25, 1.0
	v_pk_fma_f16 v111, v68, v99, v69
	v_cvt_scalef32_pk_f16_fp4 v68, v0, 1.0 op_sel:[0,1,0]
	v_cvt_scalef32_pk_f16_fp4 v0, v0, 1.0 op_sel:[1,1,0]
	v_pk_fma_f16 v71, v71, v98, 0
	v_cvt_scalef32_pk_f16_fp4 v76, v25, 1.0 op_sel:[1,0,0]
	v_pk_fma_f16 v113, v0, v99, v24
	v_cvt_scalef32_pk_f16_fp4 v0, v1, 1.0
	v_pk_fma_f16 v76, v76, v98, 0
	v_cvt_scalef32_pk_f16_fp4 v77, v25, 1.0 op_sel:[0,1,0]
	v_pk_fma_f16 v114, v0, v99, v71
	v_cvt_scalef32_pk_f16_fp4 v0, v1, 1.0 op_sel:[1,0,0]
	v_pk_fma_f16 v77, v77, v98, 0
	v_cvt_scalef32_pk_f16_fp4 v25, v25, 1.0 op_sel:[1,1,0]
	v_pk_fma_f16 v115, v0, v99, v76
	v_cvt_scalef32_pk_f16_fp4 v0, v1, 1.0 op_sel:[0,1,0]
	v_pk_fma_f16 v25, v25, v98, 0
	v_cvt_scalef32_pk_f16_fp4 v78, v26, 1.0
	v_pk_fma_f16 v116, v0, v99, v77
	v_cvt_scalef32_pk_f16_fp4 v0, v1, 1.0 op_sel:[1,1,0]
	v_pk_fma_f16 v78, v78, v98, 0
	v_cvt_scalef32_pk_f16_fp4 v79, v26, 1.0 op_sel:[1,0,0]
	v_pk_fma_f16 v117, v0, v99, v25
	v_cvt_scalef32_pk_f16_fp4 v0, v2, 1.0
	v_pk_fma_f16 v79, v79, v98, 0
	v_cvt_scalef32_pk_f16_fp4 v97, v26, 1.0 op_sel:[0,1,0]
	v_pk_fma_f16 v118, v0, v99, v78
	v_cvt_scalef32_pk_f16_fp4 v0, v2, 1.0 op_sel:[1,0,0]
	v_pk_fma_f16 v97, v97, v98, 0
	v_cvt_scalef32_pk_f16_fp4 v26, v26, 1.0 op_sel:[1,1,0]
	v_pk_fma_f16 v119, v0, v99, v79
	v_cvt_scalef32_pk_f16_fp4 v0, v2, 1.0 op_sel:[0,1,0]
	v_pk_fma_f16 v26, v26, v98, 0
	v_cvt_scalef32_pk_f16_fp4 v102, v27, 1.0
	v_pk_fma_f16 v97, v0, v99, v97
	v_cvt_scalef32_pk_f16_fp4 v0, v2, 1.0 op_sel:[1,1,0]
	v_pk_fma_f16 v102, v102, v98, 0
	v_cvt_scalef32_pk_f16_fp4 v103, v27, 1.0 op_sel:[1,0,0]
	v_pk_fma_f16 v120, v0, v99, v26
	v_cvt_scalef32_pk_f16_fp4 v0, v3, 1.0
	v_pk_fma_f16 v103, v103, v98, 0
	v_cvt_scalef32_pk_f16_fp4 v104, v27, 1.0 op_sel:[0,1,0]
	v_cvt_scalef32_pk_f16_fp4 v27, v27, 1.0 op_sel:[1,1,0]
	v_pk_fma_f16 v121, v0, v99, v102
	v_cvt_scalef32_pk_f16_fp4 v0, v3, 1.0 op_sel:[1,0,0]
	v_pk_fma_f16 v70, v70, v98, 0
	v_pk_fma_f16 v104, v104, v98, 0
	v_pk_fma_f16 v27, v27, v98, 0
	v_lshl_add_u32 v98, s24, 9, v94
	v_pk_fma_f16 v122, v0, v99, v103
	v_cvt_scalef32_pk_f16_fp4 v0, v3, 1.0 op_sel:[0,1,0]
	v_pk_fma_f16 v123, v0, v99, v104
	ds_read_b128 v[102:105], v98
	v_or_b32_e32 v96, s25, v93
	v_cvt_scalef32_pk_f16_fp4 v0, v3, 1.0 op_sel:[1,1,0]
	v_pk_fma_f16 v112, v68, v99, v70
	v_pk_fma_f16 v99, v0, v99, v27
	s_waitcnt lgkmcnt(0)
	v_add_u32_e32 v102, v102, v96
	ds_read_b128 v[106:109], v98 offset:16
	ds_read_b128 v[76:79], v98 offset:32
	ds_read_b128 v[68:71], v98 offset:48
	v_add_u32_e32 v98, v103, v96
	global_load_dwordx4 v[24:27], v102, s[12:13]
	global_load_dwordx4 v[0:3], v98, s[12:13]
	s_waitcnt vmcnt(16)
	v_cvt_scalef32_pk_f16_fp4 v102, v28, 1.0 op_sel:[1,0,0]
	v_cvt_scalef32_pk_f16_fp4 v98, v28, 1.0
	v_pk_fma_f16 v102, v102, v100, v111
	v_cvt_scalef32_pk_f16_fp4 v103, v28, 1.0 op_sel:[0,1,0]
	v_cvt_scalef32_pk_f16_fp4 v111, v29, 1.0 op_sel:[1,0,0]
	v_pk_fma_f16 v98, v98, v100, v110
	v_pk_fma_f16 v103, v103, v100, v112
	v_cvt_scalef32_pk_f16_fp4 v110, v29, 1.0
	v_pk_fma_f16 v111, v111, v100, v115
	v_cvt_scalef32_pk_f16_fp4 v112, v29, 1.0 op_sel:[0,1,0]
	v_cvt_scalef32_pk_f16_fp4 v29, v29, 1.0 op_sel:[1,1,0]
	v_cvt_scalef32_pk_f16_fp4 v115, v30, 1.0 op_sel:[0,1,0]
	v_cvt_scalef32_pk_f16_fp4 v28, v28, 1.0 op_sel:[1,1,0]
	v_pk_fma_f16 v112, v112, v100, v116
	v_pk_fma_f16 v29, v29, v100, v117
	v_pk_fma_f16 v97, v115, v100, v97
	v_cvt_scalef32_pk_f16_fp4 v115, v31, 1.0
	v_cvt_scalef32_pk_f16_fp4 v116, v31, 1.0 op_sel:[1,0,0]
	v_cvt_scalef32_pk_f16_fp4 v117, v31, 1.0 op_sel:[0,1,0]
	v_cvt_scalef32_pk_f16_fp4 v31, v31, 1.0 op_sel:[1,1,0]
	v_pk_fma_f16 v28, v28, v100, v113
	v_pk_fma_f16 v110, v110, v100, v114
	v_cvt_scalef32_pk_f16_fp4 v113, v30, 1.0
	v_cvt_scalef32_pk_f16_fp4 v114, v30, 1.0 op_sel:[1,0,0]
	v_cvt_scalef32_pk_f16_fp4 v30, v30, 1.0 op_sel:[1,1,0]
	v_pk_fma_f16 v31, v31, v100, v99
	s_waitcnt vmcnt(15)
; __device__ __forceinline__ void p8_peer_gather(Frame& F) {
;     ...
;             for (int i = 0; i < 16; ++i) { const h16x2 cf2 = __builtin_bit_cast(h16x2, cc[i]);
; #pragma unroll
;                 for (int w = 0; w < 4; ++w) { ya[4 * w] += cf2 * __builtin_amdgcn_cvt_scalef32_pk_f16_fp4(d[i][w], 1.0f, 0); ya[4 * w + 1] += cf2 * __builtin_amdgcn_cvt_scalef32_pk_f16_fp4(d[i][w], 1.0f, 1);
;                     ya[4 * w + 2] += cf2 * __builtin_amdgcn_cvt_scalef32_pk_f16_fp4(d[i][w], 1.0f, 2); ya[4 * w + 3] += cf2 * __builtin_amdgcn_cvt_scalef32_pk_f16_fp4(d[i][w], 1.0f, 3); }
;                 d[i] = *(const v4u*)(VQ + (size_t)(idx_s[nj * 128 + pg * 16 + i] + noff)); }
	v_cvt_scalef32_pk_f16_fp4 v99, v4, 1.0
	v_pk_fma_f16 v113, v113, v100, v118
	v_pk_fma_f16 v114, v114, v100, v119
	v_pk_fma_f16 v30, v30, v100, v120
	v_pk_fma_f16 v115, v115, v100, v121
	v_pk_fma_f16 v116, v116, v100, v122
	v_pk_fma_f16 v117, v117, v100, v123
	v_pk_fma_f16 v98, v99, v101, v98
	v_cvt_scalef32_pk_f16_fp4 v99, v4, 1.0 op_sel:[1,0,0]
	v_cvt_scalef32_pk_f16_fp4 v100, v4, 1.0 op_sel:[0,1,0]
	v_cvt_scalef32_pk_f16_fp4 v4, v4, 1.0 op_sel:[1,1,0]
	v_pk_fma_f16 v99, v99, v101, v102
	v_pk_fma_f16 v102, v4, v101, v28
	v_cvt_scalef32_pk_f16_fp4 v4, v5, 1.0
	v_pk_fma_f16 v100, v100, v101, v103
	v_pk_fma_f16 v103, v4, v101, v110
	v_cvt_scalef32_pk_f16_fp4 v4, v5, 1.0 op_sel:[1,0,0]
	v_pk_fma_f16 v110, v4, v101, v111
	v_cvt_scalef32_pk_f16_fp4 v4, v5, 1.0 op_sel:[0,1,0]
	v_pk_fma_f16 v111, v4, v101, v112
	v_cvt_scalef32_pk_f16_fp4 v4, v5, 1.0 op_sel:[1,1,0]
	v_pk_fma_f16 v112, v4, v101, v29
	v_cvt_scalef32_pk_f16_fp4 v4, v6, 1.0
	v_pk_fma_f16 v113, v4, v101, v113
	v_cvt_scalef32_pk_f16_fp4 v4, v6, 1.0 op_sel:[1,0,0]
	v_pk_fma_f16 v114, v4, v101, v114
	v_cvt_scalef32_pk_f16_fp4 v4, v6, 1.0 op_sel:[0,1,0]
	v_pk_fma_f16 v97, v4, v101, v97
	v_cvt_scalef32_pk_f16_fp4 v4, v6, 1.0 op_sel:[1,1,0]
	v_pk_fma_f16 v118, v4, v101, v30
	v_cvt_scalef32_pk_f16_fp4 v4, v7, 1.0
	v_pk_fma_f16 v115, v4, v101, v115
	v_cvt_scalef32_pk_f16_fp4 v4, v7, 1.0 op_sel:[1,0,0]
	v_pk_fma_f16 v116, v4, v101, v116
	v_cvt_scalef32_pk_f16_fp4 v4, v7, 1.0 op_sel:[0,1,0]
	v_pk_fma_f16 v117, v4, v101, v117
	v_cvt_scalef32_pk_f16_fp4 v4, v7, 1.0 op_sel:[1,1,0]
	v_add_u32_e32 v104, v104, v96
	v_pk_fma_f16 v101, v4, v101, v31
	v_add_u32_e32 v105, v105, v96
	global_load_dwordx4 v[28:31], v104, s[12:13]
	global_load_dwordx4 v[4:7], v105, s[12:13]
	s_waitcnt vmcnt(16)
	v_cvt_scalef32_pk_f16_fp4 v104, v36, 1.0
	v_pk_fma_f16 v98, v104, v80, v98
	v_cvt_scalef32_pk_f16_fp4 v104, v36, 1.0 op_sel:[1,0,0]
	v_pk_fma_f16 v99, v104, v80, v99
	v_cvt_scalef32_pk_f16_fp4 v104, v36, 1.0 op_sel:[0,1,0]
	v_cvt_scalef32_pk_f16_fp4 v36, v36, 1.0 op_sel:[1,1,0]
	v_pk_fma_f16 v100, v104, v80, v100
	v_pk_fma_f16 v36, v36, v80, v102
	v_cvt_scalef32_pk_f16_fp4 v102, v37, 1.0
	v_cvt_scalef32_pk_f16_fp4 v104, v37, 1.0 op_sel:[0,1,0]
	v_pk_fma_f16 v102, v102, v80, v103
	v_cvt_scalef32_pk_f16_fp4 v103, v37, 1.0 op_sel:[1,0,0]
	v_pk_fma_f16 v104, v104, v80, v111
	v_cvt_scalef32_pk_f16_fp4 v37, v37, 1.0 op_sel:[1,1,0]
	v_cvt_scalef32_pk_f16_fp4 v105, v38, 1.0
	v_cvt_scalef32_pk_f16_fp4 v111, v38, 1.0 op_sel:[0,1,0]
	v_pk_fma_f16 v103, v103, v80, v110
	v_pk_fma_f16 v37, v37, v80, v112
	v_pk_fma_f16 v105, v105, v80, v113
	v_cvt_scalef32_pk_f16_fp4 v110, v38, 1.0 op_sel:[1,0,0]
	v_pk_fma_f16 v97, v111, v80, v97
	v_cvt_scalef32_pk_f16_fp4 v38, v38, 1.0 op_sel:[1,1,0]
	v_cvt_scalef32_pk_f16_fp4 v111, v39, 1.0
	v_cvt_scalef32_pk_f16_fp4 v112, v39, 1.0 op_sel:[1,0,0]
	v_cvt_scalef32_pk_f16_fp4 v113, v39, 1.0 op_sel:[0,1,0]
	v_cvt_scalef32_pk_f16_fp4 v39, v39, 1.0 op_sel:[1,1,0]
	v_pk_fma_f16 v110, v110, v80, v114
	v_pk_fma_f16 v38, v38, v80, v118
	v_pk_fma_f16 v111, v111, v80, v115
	v_pk_fma_f16 v112, v112, v80, v116
	v_pk_fma_f16 v113, v113, v80, v117
	v_pk_fma_f16 v39, v39, v80, v101
	s_waitcnt vmcnt(15)
	v_cvt_scalef32_pk_f16_fp4 v80, v8, 1.0
	v_pk_fma_f16 v80, v80, v81, v98
	v_cvt_scalef32_pk_f16_fp4 v98, v8, 1.0 op_sel:[1,0,0]
	v_pk_fma_f16 v98, v98, v81, v99
	v_cvt_scalef32_pk_f16_fp4 v99, v8, 1.0 op_sel:[0,1,0]
	v_cvt_scalef32_pk_f16_fp4 v8, v8, 1.0 op_sel:[1,1,0]
	v_pk_fma_f16 v99, v99, v81, v100
	v_pk_fma_f16 v100, v8, v81, v36
	v_cvt_scalef32_pk_f16_fp4 v8, v9, 1.0
	v_pk_fma_f16 v101, v8, v81, v102
	v_cvt_scalef32_pk_f16_fp4 v8, v9, 1.0 op_sel:[1,0,0]
	v_pk_fma_f16 v102, v8, v81, v103
	v_cvt_scalef32_pk_f16_fp4 v8, v9, 1.0 op_sel:[0,1,0]
	v_pk_fma_f16 v103, v8, v81, v104
	v_cvt_scalef32_pk_f16_fp4 v8, v9, 1.0 op_sel:[1,1,0]
	v_pk_fma_f16 v104, v8, v81, v37
	v_cvt_scalef32_pk_f16_fp4 v8, v10, 1.0
	v_pk_fma_f16 v105, v8, v81, v105
	v_cvt_scalef32_pk_f16_fp4 v8, v10, 1.0 op_sel:[1,0,0]
	v_pk_fma_f16 v110, v8, v81, v110
	v_cvt_scalef32_pk_f16_fp4 v8, v10, 1.0 op_sel:[0,1,0]
	v_pk_fma_f16 v97, v8, v81, v97
	v_cvt_scalef32_pk_f16_fp4 v8, v10, 1.0 op_sel:[1,1,0]
	v_pk_fma_f16 v114, v8, v81, v38
	v_cvt_scalef32_pk_f16_fp4 v8, v11, 1.0
	v_pk_fma_f16 v111, v8, v81, v111
	v_cvt_scalef32_pk_f16_fp4 v8, v11, 1.0 op_sel:[1,0,0]
	v_pk_fma_f16 v112, v8, v81, v112
	v_cvt_scalef32_pk_f16_fp4 v8, v11, 1.0 op_sel:[0,1,0]
	v_pk_fma_f16 v113, v8, v81, v113
	v_cvt_scalef32_pk_f16_fp4 v8, v11, 1.0 op_sel:[1,1,0]
	s_waitcnt lgkmcnt(2)
	v_add_u32_e32 v106, v106, v96
	v_pk_fma_f16 v81, v8, v81, v39
	v_add_u32_e32 v107, v107, v96
	global_load_dwordx4 v[36:39], v106, s[12:13]
	global_load_dwordx4 v[8:11], v107, s[12:13]
	s_waitcnt vmcnt(16)
	v_cvt_scalef32_pk_f16_fp4 v106, v44, 1.0
	v_pk_fma_f16 v80, v106, v82, v80
	v_cvt_scalef32_pk_f16_fp4 v106, v44, 1.0 op_sel:[1,0,0]
	v_pk_fma_f16 v98, v106, v82, v98
	v_cvt_scalef32_pk_f16_fp4 v106, v44, 1.0 op_sel:[0,1,0]
	v_cvt_scalef32_pk_f16_fp4 v44, v44, 1.0 op_sel:[1,1,0]
	v_pk_fma_f16 v44, v44, v82, v100
	v_cvt_scalef32_pk_f16_fp4 v100, v45, 1.0
	v_pk_fma_f16 v100, v100, v82, v101
	v_cvt_scalef32_pk_f16_fp4 v101, v45, 1.0 op_sel:[1,0,0]
	v_pk_fma_f16 v101, v101, v82, v102
	v_cvt_scalef32_pk_f16_fp4 v102, v45, 1.0 op_sel:[0,1,0]
	v_pk_fma_f16 v102, v102, v82, v103
	v_cvt_scalef32_pk_f16_fp4 v103, v46, 1.0
	v_pk_fma_f16 v103, v103, v82, v105
	v_cvt_scalef32_pk_f16_fp4 v105, v46, 1.0 op_sel:[0,1,0]
	v_pk_fma_f16 v99, v106, v82, v99
	v_cvt_scalef32_pk_f16_fp4 v45, v45, 1.0 op_sel:[1,1,0]
	v_pk_fma_f16 v97, v105, v82, v97
	v_cvt_scalef32_pk_f16_fp4 v105, v47, 1.0
	v_cvt_scalef32_pk_f16_fp4 v106, v47, 1.0 op_sel:[1,0,0]
	v_cvt_scalef32_pk_f16_fp4 v107, v47, 1.0 op_sel:[0,1,0]
	v_cvt_scalef32_pk_f16_fp4 v47, v47, 1.0 op_sel:[1,1,0]
	v_pk_fma_f16 v45, v45, v82, v104
	v_cvt_scalef32_pk_f16_fp4 v104, v46, 1.0 op_sel:[1,0,0]
	v_cvt_scalef32_pk_f16_fp4 v46, v46, 1.0 op_sel:[1,1,0]
	v_pk_fma_f16 v47, v47, v82, v81
	s_waitcnt vmcnt(15)
; __device__ __forceinline__ void p8_peer_gather(Frame& F) {
;     ...
;             for (int i = 0; i < 16; ++i) { const h16x2 cf2 = __builtin_bit_cast(h16x2, cc[i]);
; #pragma unroll
;                 for (int w = 0; w < 4; ++w) { ya[4 * w] += cf2 * __builtin_amdgcn_cvt_scalef32_pk_f16_fp4(d[i][w], 1.0f, 0); ya[4 * w + 1] += cf2 * __builtin_amdgcn_cvt_scalef32_pk_f16_fp4(d[i][w], 1.0f, 1);
;                     ya[4 * w + 2] += cf2 * __builtin_amdgcn_cvt_scalef32_pk_f16_fp4(d[i][w], 1.0f, 2); ya[4 * w + 3] += cf2 * __builtin_amdgcn_cvt_scalef32_pk_f16_fp4(d[i][w], 1.0f, 3); }
;                 d[i] = *(const v4u*)(VQ + (size_t)(idx_s[nj * 128 + pg * 16 + i] + noff)); }
	v_cvt_scalef32_pk_f16_fp4 v81, v12, 1.0
	v_pk_fma_f16 v104, v104, v82, v110
	v_pk_fma_f16 v46, v46, v82, v114
	v_pk_fma_f16 v105, v105, v82, v111
	v_pk_fma_f16 v106, v106, v82, v112
	v_pk_fma_f16 v107, v107, v82, v113
	v_pk_fma_f16 v80, v81, v83, v80
	v_cvt_scalef32_pk_f16_fp4 v81, v12, 1.0 op_sel:[1,0,0]
	v_cvt_scalef32_pk_f16_fp4 v82, v12, 1.0 op_sel:[0,1,0]
	v_cvt_scalef32_pk_f16_fp4 v12, v12, 1.0 op_sel:[1,1,0]
	v_pk_fma_f16 v81, v81, v83, v98
	v_pk_fma_f16 v98, v12, v83, v44
	v_cvt_scalef32_pk_f16_fp4 v12, v13, 1.0
	v_pk_fma_f16 v82, v82, v83, v99
	v_pk_fma_f16 v99, v12, v83, v100
	v_cvt_scalef32_pk_f16_fp4 v12, v13, 1.0 op_sel:[1,0,0]
	v_pk_fma_f16 v100, v12, v83, v101
	v_cvt_scalef32_pk_f16_fp4 v12, v13, 1.0 op_sel:[0,1,0]
	v_pk_fma_f16 v101, v12, v83, v102
	v_cvt_scalef32_pk_f16_fp4 v12, v13, 1.0 op_sel:[1,1,0]
	v_pk_fma_f16 v102, v12, v83, v45
	v_cvt_scalef32_pk_f16_fp4 v12, v14, 1.0
	v_pk_fma_f16 v103, v12, v83, v103
	v_cvt_scalef32_pk_f16_fp4 v12, v14, 1.0 op_sel:[1,0,0]
	v_pk_fma_f16 v104, v12, v83, v104
	v_cvt_scalef32_pk_f16_fp4 v12, v14, 1.0 op_sel:[0,1,0]
	v_pk_fma_f16 v97, v12, v83, v97
	v_cvt_scalef32_pk_f16_fp4 v12, v14, 1.0 op_sel:[1,1,0]
	v_pk_fma_f16 v110, v12, v83, v46
	v_cvt_scalef32_pk_f16_fp4 v12, v15, 1.0
	v_pk_fma_f16 v105, v12, v83, v105
	v_cvt_scalef32_pk_f16_fp4 v12, v15, 1.0 op_sel:[1,0,0]
	v_pk_fma_f16 v106, v12, v83, v106
	v_cvt_scalef32_pk_f16_fp4 v12, v15, 1.0 op_sel:[0,1,0]
	v_pk_fma_f16 v107, v12, v83, v107
	v_cvt_scalef32_pk_f16_fp4 v12, v15, 1.0 op_sel:[1,1,0]
	v_add_u32_e32 v108, v108, v96
	v_pk_fma_f16 v83, v12, v83, v47
	v_add_u32_e32 v109, v109, v96
	global_load_dwordx4 v[44:47], v108, s[12:13]
	global_load_dwordx4 v[12:15], v109, s[12:13]
	s_waitcnt vmcnt(16)
	v_cvt_scalef32_pk_f16_fp4 v108, v48, 1.0
	v_pk_fma_f16 v80, v108, v72, v80
	v_cvt_scalef32_pk_f16_fp4 v108, v48, 1.0 op_sel:[1,0,0]
	v_pk_fma_f16 v81, v108, v72, v81
	v_cvt_scalef32_pk_f16_fp4 v108, v48, 1.0 op_sel:[0,1,0]
	v_cvt_scalef32_pk_f16_fp4 v48, v48, 1.0 op_sel:[1,1,0]
	v_pk_fma_f16 v48, v48, v72, v98
	v_cvt_scalef32_pk_f16_fp4 v98, v49, 1.0
	v_pk_fma_f16 v98, v98, v72, v99
	v_cvt_scalef32_pk_f16_fp4 v99, v49, 1.0 op_sel:[1,0,0]
	v_pk_fma_f16 v99, v99, v72, v100
	v_cvt_scalef32_pk_f16_fp4 v100, v49, 1.0 op_sel:[0,1,0]
	v_pk_fma_f16 v100, v100, v72, v101
	v_cvt_scalef32_pk_f16_fp4 v101, v50, 1.0
	v_cvt_scalef32_pk_f16_fp4 v49, v49, 1.0 op_sel:[1,1,0]
	v_pk_fma_f16 v101, v101, v72, v103
	v_cvt_scalef32_pk_f16_fp4 v103, v50, 1.0 op_sel:[0,1,0]
	v_pk_fma_f16 v49, v49, v72, v102
	v_cvt_scalef32_pk_f16_fp4 v102, v50, 1.0 op_sel:[1,0,0]
	v_pk_fma_f16 v97, v103, v72, v97
	v_cvt_scalef32_pk_f16_fp4 v103, v51, 1.0
	v_pk_fma_f16 v102, v102, v72, v104
	v_cvt_scalef32_pk_f16_fp4 v50, v50, 1.0 op_sel:[1,1,0]
	v_pk_fma_f16 v103, v103, v72, v105
	v_cvt_scalef32_pk_f16_fp4 v104, v51, 1.0 op_sel:[1,0,0]
	v_cvt_scalef32_pk_f16_fp4 v105, v51, 1.0 op_sel:[0,1,0]
	v_cvt_scalef32_pk_f16_fp4 v51, v51, 1.0 op_sel:[1,1,0]
	v_pk_fma_f16 v82, v108, v72, v82
	v_pk_fma_f16 v50, v50, v72, v110
	v_pk_fma_f16 v104, v104, v72, v106
	v_pk_fma_f16 v105, v105, v72, v107
	v_pk_fma_f16 v51, v51, v72, v83
	s_waitcnt vmcnt(15)
	v_cvt_scalef32_pk_f16_fp4 v72, v16, 1.0
	v_pk_fma_f16 v72, v72, v73, v80
	v_cvt_scalef32_pk_f16_fp4 v80, v16, 1.0 op_sel:[1,0,0]
	v_pk_fma_f16 v80, v80, v73, v81
	v_cvt_scalef32_pk_f16_fp4 v81, v16, 1.0 op_sel:[0,1,0]
	v_cvt_scalef32_pk_f16_fp4 v16, v16, 1.0 op_sel:[1,1,0]
	v_pk_fma_f16 v81, v81, v73, v82
	v_pk_fma_f16 v82, v16, v73, v48
	v_cvt_scalef32_pk_f16_fp4 v16, v17, 1.0
	v_pk_fma_f16 v83, v16, v73, v98
	v_cvt_scalef32_pk_f16_fp4 v16, v17, 1.0 op_sel:[1,0,0]
	v_pk_fma_f16 v98, v16, v73, v99
	v_cvt_scalef32_pk_f16_fp4 v16, v17, 1.0 op_sel:[0,1,0]
	v_pk_fma_f16 v99, v16, v73, v100
	v_cvt_scalef32_pk_f16_fp4 v16, v17, 1.0 op_sel:[1,1,0]
	v_pk_fma_f16 v100, v16, v73, v49
	v_cvt_scalef32_pk_f16_fp4 v16, v18, 1.0
	v_pk_fma_f16 v101, v16, v73, v101
	v_cvt_scalef32_pk_f16_fp4 v16, v18, 1.0 op_sel:[1,0,0]
	v_pk_fma_f16 v102, v16, v73, v102
	v_cvt_scalef32_pk_f16_fp4 v16, v18, 1.0 op_sel:[0,1,0]
	v_pk_fma_f16 v97, v16, v73, v97
	v_cvt_scalef32_pk_f16_fp4 v16, v18, 1.0 op_sel:[1,1,0]
	v_pk_fma_f16 v106, v16, v73, v50
	v_cvt_scalef32_pk_f16_fp4 v16, v19, 1.0
	v_pk_fma_f16 v103, v16, v73, v103
	v_cvt_scalef32_pk_f16_fp4 v16, v19, 1.0 op_sel:[1,0,0]
	v_pk_fma_f16 v104, v16, v73, v104
	v_cvt_scalef32_pk_f16_fp4 v16, v19, 1.0 op_sel:[0,1,0]
	v_pk_fma_f16 v105, v16, v73, v105
	v_cvt_scalef32_pk_f16_fp4 v16, v19, 1.0 op_sel:[1,1,0]
	s_waitcnt lgkmcnt(1)
	v_add_u32_e32 v76, v76, v96
	v_pk_fma_f16 v73, v16, v73, v51
	v_add_u32_e32 v77, v77, v96
	global_load_dwordx4 v[48:51], v76, s[12:13]
	global_load_dwordx4 v[16:19], v77, s[12:13]
	s_waitcnt vmcnt(16)
	v_cvt_scalef32_pk_f16_fp4 v76, v52, 1.0
	v_pk_fma_f16 v72, v76, v74, v72
	v_cvt_scalef32_pk_f16_fp4 v76, v52, 1.0 op_sel:[1,0,0]
	v_cvt_scalef32_pk_f16_fp4 v77, v52, 1.0 op_sel:[0,1,0]
	v_cvt_scalef32_pk_f16_fp4 v52, v52, 1.0 op_sel:[1,1,0]
	v_pk_fma_f16 v76, v76, v74, v80
	v_pk_fma_f16 v52, v52, v74, v82
	v_cvt_scalef32_pk_f16_fp4 v80, v53, 1.0
	v_cvt_scalef32_pk_f16_fp4 v82, v53, 1.0 op_sel:[0,1,0]
	v_pk_fma_f16 v77, v77, v74, v81
	v_pk_fma_f16 v80, v80, v74, v83
	v_cvt_scalef32_pk_f16_fp4 v81, v53, 1.0 op_sel:[1,0,0]
	v_pk_fma_f16 v82, v82, v74, v99
	v_cvt_scalef32_pk_f16_fp4 v53, v53, 1.0 op_sel:[1,1,0]
	v_cvt_scalef32_pk_f16_fp4 v83, v54, 1.0
	v_cvt_scalef32_pk_f16_fp4 v99, v54, 1.0 op_sel:[0,1,0]
	v_pk_fma_f16 v53, v53, v74, v100
	v_pk_fma_f16 v83, v83, v74, v101
	v_pk_fma_f16 v97, v99, v74, v97
	v_cvt_scalef32_pk_f16_fp4 v99, v55, 1.0
	v_cvt_scalef32_pk_f16_fp4 v100, v55, 1.0 op_sel:[1,0,0]
	v_cvt_scalef32_pk_f16_fp4 v101, v55, 1.0 op_sel:[0,1,0]
	v_cvt_scalef32_pk_f16_fp4 v55, v55, 1.0 op_sel:[1,1,0]
	v_pk_fma_f16 v81, v81, v74, v98
	v_cvt_scalef32_pk_f16_fp4 v98, v54, 1.0 op_sel:[1,0,0]
	v_cvt_scalef32_pk_f16_fp4 v54, v54, 1.0 op_sel:[1,1,0]
	v_pk_fma_f16 v55, v55, v74, v73
	s_waitcnt vmcnt(15)
; __device__ __forceinline__ void p8_peer_gather(Frame& F) {
;     ...
;             for (int i = 0; i < 16; ++i) { const h16x2 cf2 = __builtin_bit_cast(h16x2, cc[i]);
; #pragma unroll
;                 for (int w = 0; w < 4; ++w) { ya[4 * w] += cf2 * __builtin_amdgcn_cvt_scalef32_pk_f16_fp4(d[i][w], 1.0f, 0); ya[4 * w + 1] += cf2 * __builtin_amdgcn_cvt_scalef32_pk_f16_fp4(d[i][w], 1.0f, 1);
;                     ya[4 * w + 2] += cf2 * __builtin_amdgcn_cvt_scalef32_pk_f16_fp4(d[i][w], 1.0f, 2); ya[4 * w + 3] += cf2 * __builtin_amdgcn_cvt_scalef32_pk_f16_fp4(d[i][w], 1.0f, 3); }
;                 d[i] = *(const v4u*)(VQ + (size_t)(idx_s[nj * 128 + pg * 16 + i] + noff)); }
	v_cvt_scalef32_pk_f16_fp4 v73, v20, 1.0
	v_pk_fma_f16 v98, v98, v74, v102
	v_pk_fma_f16 v54, v54, v74, v106
	v_pk_fma_f16 v99, v99, v74, v103
	v_pk_fma_f16 v100, v100, v74, v104
	v_pk_fma_f16 v101, v101, v74, v105
	v_pk_fma_f16 v72, v73, v75, v72
	v_cvt_scalef32_pk_f16_fp4 v73, v20, 1.0 op_sel:[1,0,0]
	v_cvt_scalef32_pk_f16_fp4 v74, v20, 1.0 op_sel:[0,1,0]
	v_cvt_scalef32_pk_f16_fp4 v20, v20, 1.0 op_sel:[1,1,0]
	v_pk_fma_f16 v73, v73, v75, v76
	v_pk_fma_f16 v76, v20, v75, v52
	v_cvt_scalef32_pk_f16_fp4 v20, v21, 1.0
	v_pk_fma_f16 v74, v74, v75, v77
	v_pk_fma_f16 v77, v20, v75, v80
	v_cvt_scalef32_pk_f16_fp4 v20, v21, 1.0 op_sel:[1,0,0]
	v_pk_fma_f16 v80, v20, v75, v81
	v_cvt_scalef32_pk_f16_fp4 v20, v21, 1.0 op_sel:[0,1,0]
	v_pk_fma_f16 v81, v20, v75, v82
	v_cvt_scalef32_pk_f16_fp4 v20, v21, 1.0 op_sel:[1,1,0]
	v_pk_fma_f16 v82, v20, v75, v53
	v_cvt_scalef32_pk_f16_fp4 v20, v22, 1.0
	v_pk_fma_f16 v83, v20, v75, v83
	v_cvt_scalef32_pk_f16_fp4 v20, v22, 1.0 op_sel:[1,0,0]
	v_pk_fma_f16 v98, v20, v75, v98
	v_cvt_scalef32_pk_f16_fp4 v20, v22, 1.0 op_sel:[0,1,0]
	v_pk_fma_f16 v97, v20, v75, v97
	v_cvt_scalef32_pk_f16_fp4 v20, v22, 1.0 op_sel:[1,1,0]
	v_pk_fma_f16 v102, v20, v75, v54
	v_cvt_scalef32_pk_f16_fp4 v20, v23, 1.0
	v_pk_fma_f16 v99, v20, v75, v99
	v_cvt_scalef32_pk_f16_fp4 v20, v23, 1.0 op_sel:[1,0,0]
	v_pk_fma_f16 v100, v20, v75, v100
	v_cvt_scalef32_pk_f16_fp4 v20, v23, 1.0 op_sel:[0,1,0]
	v_pk_fma_f16 v101, v20, v75, v101
	v_cvt_scalef32_pk_f16_fp4 v20, v23, 1.0 op_sel:[1,1,0]
	v_add_u32_e32 v78, v78, v96
	v_pk_fma_f16 v75, v20, v75, v55
	v_add_u32_e32 v79, v79, v96
	global_load_dwordx4 v[52:55], v78, s[12:13]
	global_load_dwordx4 v[20:23], v79, s[12:13]
	s_waitcnt vmcnt(16)
	v_cvt_scalef32_pk_f16_fp4 v78, v56, 1.0
	v_pk_fma_f16 v72, v78, v64, v72
	v_cvt_scalef32_pk_f16_fp4 v78, v56, 1.0 op_sel:[1,0,0]
	v_pk_fma_f16 v73, v78, v64, v73
	v_cvt_scalef32_pk_f16_fp4 v78, v56, 1.0 op_sel:[0,1,0]
	v_cvt_scalef32_pk_f16_fp4 v56, v56, 1.0 op_sel:[1,1,0]
	v_pk_fma_f16 v74, v78, v64, v74
	v_pk_fma_f16 v56, v56, v64, v76
	v_cvt_scalef32_pk_f16_fp4 v76, v57, 1.0
	v_cvt_scalef32_pk_f16_fp4 v78, v57, 1.0 op_sel:[0,1,0]
	v_pk_fma_f16 v76, v76, v64, v77
	v_cvt_scalef32_pk_f16_fp4 v77, v57, 1.0 op_sel:[1,0,0]
	v_pk_fma_f16 v78, v78, v64, v81
	v_cvt_scalef32_pk_f16_fp4 v57, v57, 1.0 op_sel:[1,1,0]
	v_cvt_scalef32_pk_f16_fp4 v79, v58, 1.0
	v_cvt_scalef32_pk_f16_fp4 v81, v58, 1.0 op_sel:[0,1,0]
	v_pk_fma_f16 v77, v77, v64, v80
	v_pk_fma_f16 v57, v57, v64, v82
	v_pk_fma_f16 v79, v79, v64, v83
	v_cvt_scalef32_pk_f16_fp4 v80, v58, 1.0 op_sel:[1,0,0]
	v_pk_fma_f16 v81, v81, v64, v97
	v_cvt_scalef32_pk_f16_fp4 v58, v58, 1.0 op_sel:[1,1,0]
	v_cvt_scalef32_pk_f16_fp4 v82, v59, 1.0
	v_cvt_scalef32_pk_f16_fp4 v83, v59, 1.0 op_sel:[1,0,0]
	v_cvt_scalef32_pk_f16_fp4 v97, v59, 1.0 op_sel:[0,1,0]
	v_cvt_scalef32_pk_f16_fp4 v59, v59, 1.0 op_sel:[1,1,0]
	v_pk_fma_f16 v80, v80, v64, v98
	v_pk_fma_f16 v58, v58, v64, v102
	v_pk_fma_f16 v82, v82, v64, v99
	v_pk_fma_f16 v83, v83, v64, v100
	v_pk_fma_f16 v97, v97, v64, v101
	v_pk_fma_f16 v59, v59, v64, v75
	s_waitcnt vmcnt(15)
	v_cvt_scalef32_pk_f16_fp4 v64, v32, 1.0
	v_pk_fma_f16 v64, v64, v65, v72
	v_cvt_scalef32_pk_f16_fp4 v72, v32, 1.0 op_sel:[1,0,0]
	v_pk_fma_f16 v72, v72, v65, v73
	v_cvt_scalef32_pk_f16_fp4 v73, v32, 1.0 op_sel:[0,1,0]
	v_cvt_scalef32_pk_f16_fp4 v32, v32, 1.0 op_sel:[1,1,0]
	v_pk_fma_f16 v73, v73, v65, v74
	v_pk_fma_f16 v74, v32, v65, v56
	v_cvt_scalef32_pk_f16_fp4 v32, v33, 1.0
	v_pk_fma_f16 v75, v32, v65, v76
	v_cvt_scalef32_pk_f16_fp4 v32, v33, 1.0 op_sel:[1,0,0]
	v_pk_fma_f16 v76, v32, v65, v77
	v_cvt_scalef32_pk_f16_fp4 v32, v33, 1.0 op_sel:[0,1,0]
	v_pk_fma_f16 v77, v32, v65, v78
	v_cvt_scalef32_pk_f16_fp4 v32, v33, 1.0 op_sel:[1,1,0]
	v_pk_fma_f16 v78, v32, v65, v57
	v_cvt_scalef32_pk_f16_fp4 v32, v34, 1.0
	v_pk_fma_f16 v79, v32, v65, v79
	v_cvt_scalef32_pk_f16_fp4 v32, v34, 1.0 op_sel:[1,0,0]
	v_pk_fma_f16 v80, v32, v65, v80
	v_cvt_scalef32_pk_f16_fp4 v32, v34, 1.0 op_sel:[0,1,0]
	v_pk_fma_f16 v81, v32, v65, v81
	v_cvt_scalef32_pk_f16_fp4 v32, v34, 1.0 op_sel:[1,1,0]
	v_pk_fma_f16 v98, v32, v65, v58
	v_cvt_scalef32_pk_f16_fp4 v32, v35, 1.0
	v_pk_fma_f16 v82, v32, v65, v82
	v_cvt_scalef32_pk_f16_fp4 v32, v35, 1.0 op_sel:[1,0,0]
	v_pk_fma_f16 v83, v32, v65, v83
	v_cvt_scalef32_pk_f16_fp4 v32, v35, 1.0 op_sel:[0,1,0]
	v_pk_fma_f16 v97, v32, v65, v97
	v_cvt_scalef32_pk_f16_fp4 v32, v35, 1.0 op_sel:[1,1,0]
	s_waitcnt lgkmcnt(0)
; __device__ __forceinline__ float xor8(float v) { return dppf<0x128>(v); }
; __device__ __forceinline__ float xor16(float v) { return __builtin_bit_cast(float, __builtin_amdgcn_ds_swizzle(__builtin_bit_cast(int, v), 0x401F)); }
; __device__ __forceinline__ void p8_peer_gather(Frame& F) {
;     ...
;             for (int i = 0; i < 16; ++i) { const h16x2 cf2 = __builtin_bit_cast(h16x2, cc[i]);
; #pragma unroll
;                 for (int w = 0; w < 4; ++w) { ya[4 * w] += cf2 * __builtin_amdgcn_cvt_scalef32_pk_f16_fp4(d[i][w], 1.0f, 0); ya[4 * w + 1] += cf2 * __builtin_amdgcn_cvt_scalef32_pk_f16_fp4(d[i][w], 1.0f, 1);
;                     ya[4 * w + 2] += cf2 * __builtin_amdgcn_cvt_scalef32_pk_f16_fp4(d[i][w], 1.0f, 2); ya[4 * w + 3] += cf2 * __builtin_amdgcn_cvt_scalef32_pk_f16_fp4(d[i][w], 1.0f, 3); }
;                 d[i] = *(const v4u*)(VQ + (size_t)(idx_s[nj * 128 + pg * 16 + i] + noff)); }
;             h16x2 tt[8];
; #pragma unroll
;             for (int e = 0; e < 8; ++e) {
;                 const auto rr = __builtin_amdgcn_permlane32_swap(__builtin_bit_cast(unsigned, ya[e]), __builtin_bit_cast(unsigned, ya[e + 8]), false, false);
;                 h16x2 t = __builtin_bit_cast(h16x2, (unsigned)rr[0]) + __builtin_bit_cast(h16x2, (unsigned)rr[1]);
;                 t += __builtin_bit_cast(h16x2, xor16(__builtin_bit_cast(float, t)));
;                 t += __builtin_bit_cast(h16x2, xor8(__builtin_bit_cast(float, t)));
;                 tt[e] = t; }
;             const int kq = pg & 3;
;             const h16x2 ta = kq == 0 ? tt[0] : kq == 1 ? tt[2] : kq == 2 ? tt[4] : tt[6], tb = kq == 0 ? tt[1] : kq == 1 ? tt[3] : kq == 2 ? tt[5] : tt[7];
	v_add_u32_e32 v68, v68, v96
	v_pk_fma_f16 v65, v32, v65, v59
	v_add_u32_e32 v69, v69, v96
	global_load_dwordx4 v[56:59], v68, s[12:13]
	global_load_dwordx4 v[32:35], v69, s[12:13]
	s_waitcnt vmcnt(16)
	v_cvt_scalef32_pk_f16_fp4 v68, v60, 1.0
	v_add_u32_e32 v70, v70, v96
	v_pk_fma_f16 v64, v68, v66, v64
	v_cvt_scalef32_pk_f16_fp4 v68, v60, 1.0 op_sel:[1,0,0]
	v_cvt_scalef32_pk_f16_fp4 v69, v60, 1.0 op_sel:[0,1,0]
	v_cvt_scalef32_pk_f16_fp4 v99, v60, 1.0 op_sel:[1,1,0]
	v_cvt_scalef32_pk_f16_fp4 v100, v61, 1.0
	v_cvt_scalef32_pk_f16_fp4 v101, v61, 1.0 op_sel:[1,0,0]
	v_cvt_scalef32_pk_f16_fp4 v102, v61, 1.0 op_sel:[0,1,0]
	v_cvt_scalef32_pk_f16_fp4 v103, v61, 1.0 op_sel:[1,1,0]
	v_cvt_scalef32_pk_f16_fp4 v104, v62, 1.0
	v_cvt_scalef32_pk_f16_fp4 v105, v62, 1.0 op_sel:[1,0,0]
	v_cvt_scalef32_pk_f16_fp4 v106, v62, 1.0 op_sel:[0,1,0]
	v_cvt_scalef32_pk_f16_fp4 v107, v62, 1.0 op_sel:[1,1,0]
	v_cvt_scalef32_pk_f16_fp4 v108, v63, 1.0
	v_cvt_scalef32_pk_f16_fp4 v109, v63, 1.0 op_sel:[1,0,0]
	v_cvt_scalef32_pk_f16_fp4 v110, v63, 1.0 op_sel:[0,1,0]
	v_cvt_scalef32_pk_f16_fp4 v111, v63, 1.0 op_sel:[1,1,0]
	s_waitcnt vmcnt(15)
	v_cvt_scalef32_pk_f16_fp4 v112, v40, 1.0
	v_cvt_scalef32_pk_f16_fp4 v113, v40, 1.0 op_sel:[1,0,0]
	v_cvt_scalef32_pk_f16_fp4 v114, v40, 1.0 op_sel:[0,1,0]
	v_cvt_scalef32_pk_f16_fp4 v115, v40, 1.0 op_sel:[1,1,0]
	v_cvt_scalef32_pk_f16_fp4 v116, v41, 1.0
	v_cvt_scalef32_pk_f16_fp4 v117, v41, 1.0 op_sel:[1,0,0]
	v_cvt_scalef32_pk_f16_fp4 v118, v41, 1.0 op_sel:[0,1,0]
	v_cvt_scalef32_pk_f16_fp4 v119, v41, 1.0 op_sel:[1,1,0]
	v_cvt_scalef32_pk_f16_fp4 v120, v42, 1.0
	v_cvt_scalef32_pk_f16_fp4 v121, v42, 1.0 op_sel:[1,0,0]
	v_cvt_scalef32_pk_f16_fp4 v122, v42, 1.0 op_sel:[0,1,0]
	v_cvt_scalef32_pk_f16_fp4 v123, v42, 1.0 op_sel:[1,1,0]
	v_cvt_scalef32_pk_f16_fp4 v124, v43, 1.0
	v_cvt_scalef32_pk_f16_fp4 v125, v43, 1.0 op_sel:[1,0,0]
	v_cvt_scalef32_pk_f16_fp4 v126, v43, 1.0 op_sel:[0,1,0]
	v_cvt_scalef32_pk_f16_fp4 v127, v43, 1.0 op_sel:[1,1,0]
	v_add_u32_e32 v71, v71, v96
	global_load_dwordx4 v[60:63], v70, s[12:13]
	global_load_dwordx4 v[40:43], v71, s[12:13]
	v_pk_fma_f16 v68, v68, v66, v72
	v_pk_fma_f16 v69, v69, v66, v73
	v_pk_fma_f16 v70, v99, v66, v74
	v_pk_fma_f16 v71, v100, v66, v75
	v_pk_fma_f16 v72, v101, v66, v76
	v_pk_fma_f16 v73, v102, v66, v77
	v_pk_fma_f16 v75, v104, v66, v79
	v_pk_fma_f16 v74, v103, v66, v78
	v_pk_fma_f16 v76, v105, v66, v80
	v_pk_fma_f16 v77, v106, v66, v81
	v_pk_fma_f16 v78, v107, v66, v98
	v_pk_fma_f16 v79, v108, v66, v82
	v_pk_fma_f16 v80, v109, v66, v83
	v_pk_fma_f16 v81, v110, v66, v97
	v_pk_fma_f16 v65, v111, v66, v65
	v_pk_fma_f16 v64, v112, v67, v64
	v_pk_fma_f16 v66, v113, v67, v68
	v_pk_fma_f16 v68, v114, v67, v69
	v_pk_fma_f16 v69, v115, v67, v70
	v_pk_fma_f16 v70, v116, v67, v71
	v_pk_fma_f16 v71, v117, v67, v72
	v_pk_fma_f16 v72, v118, v67, v73
	v_pk_fma_f16 v73, v120, v67, v75
	v_pk_fma_f16 v82, v119, v67, v74
	v_pk_fma_f16 v74, v121, v67, v76
	v_pk_fma_f16 v76, v123, v67, v78
	v_pk_fma_f16 v75, v122, v67, v77
	v_pk_fma_f16 v83, v127, v67, v65
	v_pk_fma_f16 v77, v124, v67, v79
	v_pk_fma_f16 v80, v125, v67, v80
	v_pk_fma_f16 v81, v126, v67, v81
	v_permlane32_swap_b32_e32 v64, v73
	v_permlane32_swap_b32_e32 v66, v74
	v_permlane32_swap_b32_e32 v68, v75
	v_permlane32_swap_b32_e32 v69, v76
	v_permlane32_swap_b32_e32 v70, v77
	v_permlane32_swap_b32_e32 v71, v80
	v_permlane32_swap_b32_e32 v72, v81
	v_permlane32_swap_b32_e32 v82, v83
	v_pk_add_f16 v64, v64, v73
	v_pk_add_f16 v66, v66, v74
	v_pk_add_f16 v68, v68, v75
	v_pk_add_f16 v69, v69, v76
	v_pk_add_f16 v70, v70, v77
	v_pk_add_f16 v71, v71, v80
	v_pk_add_f16 v72, v72, v81
	v_pk_add_f16 v82, v82, v83
	v_permlane16_swap_b32_e32 v64, v70
	v_permlane16_swap_b32_e32 v66, v71
	v_permlane16_swap_b32_e32 v68, v72
	v_permlane16_swap_b32_e32 v69, v82
	v_pk_add_f16 v64, v64, v70
	v_pk_add_f16 v66, v66, v71
	v_pk_add_f16 v68, v68, v72
	v_pk_add_f16 v69, v69, v82
	v_cndmask_b32_e64 v73, v68, v64, s[42:43]
	v_cndmask_b32_e64 v74, v69, v66, s[42:43]
	v_cndmask_b32_e64 v75, v64, v68, s[42:43]
	v_cndmask_b32_e64 v76, v66, v69, s[42:43]
	v_mov_b32_dpp v77, v73 row_ror:8 row_mask:0xf bank_mask:0xf bound_ctrl:1
	v_mov_b32_dpp v80, v74 row_ror:8 row_mask:0xf bank_mask:0xf bound_ctrl:1
	v_pk_add_f16 v68, v75, v77
	v_pk_add_f16 v69, v76, v80
	s_branch .LBB0_2585
